# NSA top-k block selection rewritten: lane-parallel insertion select (exact top-13, lowest-index ties) instead of 13 serial wave-argmax rounds per query
# speedup vs baseline: 1.0263x; 1.0161x over previous
; DI void nsa_item(const Params& p, int bk, int qb, char* smem, float Mb) {
;     ...
;         for (int qi = 0; qi < 16; qi += 4) {
; #pragma unroll
;             for (int u = 0; u < 4; ++u)
;                 if (lane < 16) {
;                     int v = -1;
;                     if (ncand <= need && lane >= nforced && lane - nforced < ncand) v = lane - nforced + 1;
;                     sel[(qi + u) * 16 + lane] = v;
;                 }
;             if (ncand > need) {
;                 float key[4][4];
; #pragma unroll
;                 for (int u = 0; u < 4; ++u)
; #pragma unroll
;                     for (int r = 0; r < 4; ++r) {
;                         const int j = lane + 64 * r;
;                         key[u][r] = (j >= 1 && j <= cur - 2) ? imp[(qi + u) * 260 + j] : -1.f;
;                     }
;                 for (int s = 0; s < need; ++s) {
; #pragma unroll
;                     for (int u = 0; u < 4; ++u) {
;                         const float best = wave_max(fmaxf(fmaxf(key[u][0], key[u][1]), fmaxf(key[u][2], key[u][3])));
;                         int jstar = 1 << 20;
; #pragma unroll
;                         for (int r = 3; r >= 0; --r) {
;                             const unsigned long long bm = __ballot(key[u][r] == best);
;                             if (bm) jstar = 64 * r + (int)__builtin_ctzll(bm);
;                         }
; #pragma unroll
;                         for (int r = 0; r < 4; ++r) if (lane + 64 * r == jstar) key[u][r] = -1.f;
;                         if (lane == 0) sel[(qi + u) * 16 + nforced + s] = jstar;
;                     }
;                 }
.LBB0_481:
	s_or_b64 exec, exec, s[14:15]
	s_mov_b64 s[18:19], 0
	s_branch .LBB0_478
.LBB0_524:
	s_and_b64 s[24:25], s[4:5], exec
	s_cbranch_scc0 .Ltopk_skip
	s_mov_b64 s[20:21], vcc
	s_mov_b64 s[22:23], exec
	v_and_b32_e32 v28, 15, v146
	v_lshrrev_b32_e32 v29, 4, v146
	v_mul_u32_u24_e32 v30, 0x410, v28
	v_lshl_add_u32 v30, v29, 8, v30
	v_add_u32_e32 v30, s90, v30
	v_lshlrev_b32_e32 v31, 6, v29
	v_add_u32_e32 v32, -2, v238
	v_mov_b32_e32 v33, -1.0
	v_mov_b32_e32 v34, -1.0
	v_mov_b32_e32 v35, -1.0
	v_mov_b32_e32 v36, -1.0
	v_mov_b32_e32 v37, -1.0
	v_mov_b32_e32 v38, -1.0
	v_mov_b32_e32 v39, -1.0
	v_mov_b32_e32 v40, -1.0
	v_mov_b32_e32 v41, -1.0
	v_mov_b32_e32 v42, -1.0
	v_mov_b32_e32 v43, -1.0
	v_mov_b32_e32 v44, -1.0
	v_mov_b32_e32 v45, -1.0
	v_mov_b32_e32 v46, 0
	v_mov_b32_e32 v47, 0
	v_mov_b32_e32 v48, 0
	v_mov_b32_e32 v49, 0
	v_mov_b32_e32 v50, 0
	v_mov_b32_e32 v51, 0
	v_mov_b32_e32 v52, 0
	v_mov_b32_e32 v53, 0
	v_mov_b32_e32 v54, 0
	v_mov_b32_e32 v55, 0
	v_mov_b32_e32 v56, 0
	v_mov_b32_e32 v57, 0
	v_mov_b32_e32 v58, 0
	s_mov_b32 s26, 0
.Ltopk_loop:
	ds_read_b128 v[8:11], v30
	v_add_u32_e32 v30, 16, v30
	s_waitcnt lgkmcnt(0)
	v_add_u32_e32 v13, -1, v31
	v_cmp_gt_u32_e64 s[18:19], v32, v13
	v_mov_b32_e32 v13, v31
	s_nop 0
	v_cndmask_b32_e64 v12, -1.0, v8, s[18:19]
	v_cmp_gt_f32_e64 vcc, v12, v33
	s_nop 1
	v_cndmask_b32_e64 v14, v12, v33, vcc
	v_cmp_gt_f32_e64 s[14:15], v14, v34
	v_cndmask_b32_e64 v33, v33, v12, vcc
	v_cndmask_b32_e64 v15, v13, v46, vcc
	v_cndmask_b32_e64 v46, v46, v13, vcc
	v_cndmask_b32_e64 v12, v14, v34, s[14:15]
	v_cmp_gt_f32_e64 vcc, v12, v35
	v_cndmask_b32_e64 v34, v34, v14, s[14:15]
	v_cndmask_b32_e64 v13, v15, v47, s[14:15]
	v_cndmask_b32_e64 v47, v47, v15, s[14:15]
	v_cndmask_b32_e64 v14, v12, v35, vcc
	v_cmp_gt_f32_e64 s[14:15], v14, v36
	v_cndmask_b32_e64 v35, v35, v12, vcc
	v_cndmask_b32_e64 v15, v13, v48, vcc
	v_cndmask_b32_e64 v48, v48, v13, vcc
	v_cndmask_b32_e64 v12, v14, v36, s[14:15]
	v_cmp_gt_f32_e64 vcc, v12, v37
	v_cndmask_b32_e64 v36, v36, v14, s[14:15]
	v_cndmask_b32_e64 v13, v15, v49, s[14:15]
	v_cndmask_b32_e64 v49, v49, v15, s[14:15]
	v_cndmask_b32_e64 v14, v12, v37, vcc
	v_cmp_gt_f32_e64 s[14:15], v14, v38
	v_cndmask_b32_e64 v37, v37, v12, vcc
	v_cndmask_b32_e64 v15, v13, v50, vcc
	v_cndmask_b32_e64 v50, v50, v13, vcc
	v_cndmask_b32_e64 v12, v14, v38, s[14:15]
	v_cmp_gt_f32_e64 vcc, v12, v39
	v_cndmask_b32_e64 v38, v38, v14, s[14:15]
	v_cndmask_b32_e64 v13, v15, v51, s[14:15]
	v_cndmask_b32_e64 v51, v51, v15, s[14:15]
	v_cndmask_b32_e64 v14, v12, v39, vcc
	v_cmp_gt_f32_e64 s[14:15], v14, v40
	v_cndmask_b32_e64 v39, v39, v12, vcc
	v_cndmask_b32_e64 v15, v13, v52, vcc
	v_cndmask_b32_e64 v52, v52, v13, vcc
	v_cndmask_b32_e64 v12, v14, v40, s[14:15]
	v_cmp_gt_f32_e64 vcc, v12, v41
	v_cndmask_b32_e64 v40, v40, v14, s[14:15]
	v_cndmask_b32_e64 v13, v15, v53, s[14:15]
	v_cndmask_b32_e64 v53, v53, v15, s[14:15]
	v_cndmask_b32_e64 v14, v12, v41, vcc
	v_cmp_gt_f32_e64 s[14:15], v14, v42
	v_cndmask_b32_e64 v41, v41, v12, vcc
	v_cndmask_b32_e64 v15, v13, v54, vcc
	v_cndmask_b32_e64 v54, v54, v13, vcc
	v_cndmask_b32_e64 v12, v14, v42, s[14:15]
	v_cmp_gt_f32_e64 vcc, v12, v43
	v_cndmask_b32_e64 v42, v42, v14, s[14:15]
	v_cndmask_b32_e64 v13, v15, v55, s[14:15]
	v_cndmask_b32_e64 v55, v55, v15, s[14:15]
	v_cndmask_b32_e64 v14, v12, v43, vcc
	v_cmp_gt_f32_e64 s[14:15], v14, v44
	v_cndmask_b32_e64 v43, v43, v12, vcc
	v_cndmask_b32_e64 v15, v13, v56, vcc
	v_cndmask_b32_e64 v56, v56, v13, vcc
	v_cndmask_b32_e64 v12, v14, v44, s[14:15]
	v_cmp_gt_f32_e64 vcc, v12, v45
	v_cndmask_b32_e64 v44, v44, v14, s[14:15]
	v_cndmask_b32_e64 v13, v15, v57, s[14:15]
	v_cndmask_b32_e64 v57, v57, v15, s[14:15]
	v_cndmask_b32_e64 v14, v12, v45, vcc
	s_nop 0
	v_cndmask_b32_e64 v45, v45, v12, vcc
	v_cndmask_b32_e64 v58, v58, v13, vcc
	v_mov_b32_e32 v13, v31
	v_cmp_gt_u32_e64 s[18:19], v32, v13
	v_add_u32_e32 v13, 1, v31
	s_nop 0
	v_cndmask_b32_e64 v12, -1.0, v9, s[18:19]
	v_cmp_gt_f32_e64 vcc, v12, v33
	s_nop 1
	v_cndmask_b32_e64 v14, v12, v33, vcc
	v_cmp_gt_f32_e64 s[14:15], v14, v34
	v_cndmask_b32_e64 v33, v33, v12, vcc
	v_cndmask_b32_e64 v15, v13, v46, vcc
	v_cndmask_b32_e64 v46, v46, v13, vcc
	v_cndmask_b32_e64 v12, v14, v34, s[14:15]
	v_cmp_gt_f32_e64 vcc, v12, v35
	v_cndmask_b32_e64 v34, v34, v14, s[14:15]
	v_cndmask_b32_e64 v13, v15, v47, s[14:15]
	v_cndmask_b32_e64 v47, v47, v15, s[14:15]
	v_cndmask_b32_e64 v14, v12, v35, vcc
	v_cmp_gt_f32_e64 s[14:15], v14, v36
	v_cndmask_b32_e64 v35, v35, v12, vcc
	v_cndmask_b32_e64 v15, v13, v48, vcc
	v_cndmask_b32_e64 v48, v48, v13, vcc
	v_cndmask_b32_e64 v12, v14, v36, s[14:15]
	v_cmp_gt_f32_e64 vcc, v12, v37
	v_cndmask_b32_e64 v36, v36, v14, s[14:15]
	v_cndmask_b32_e64 v13, v15, v49, s[14:15]
	v_cndmask_b32_e64 v49, v49, v15, s[14:15]
	v_cndmask_b32_e64 v14, v12, v37, vcc
	v_cmp_gt_f32_e64 s[14:15], v14, v38
	v_cndmask_b32_e64 v37, v37, v12, vcc
	v_cndmask_b32_e64 v15, v13, v50, vcc
	v_cndmask_b32_e64 v50, v50, v13, vcc
	v_cndmask_b32_e64 v12, v14, v38, s[14:15]
	v_cmp_gt_f32_e64 vcc, v12, v39
	v_cndmask_b32_e64 v38, v38, v14, s[14:15]
	v_cndmask_b32_e64 v13, v15, v51, s[14:15]
	v_cndmask_b32_e64 v51, v51, v15, s[14:15]
	v_cndmask_b32_e64 v14, v12, v39, vcc
	v_cmp_gt_f32_e64 s[14:15], v14, v40
	v_cndmask_b32_e64 v39, v39, v12, vcc
	v_cndmask_b32_e64 v15, v13, v52, vcc
	v_cndmask_b32_e64 v52, v52, v13, vcc
	v_cndmask_b32_e64 v12, v14, v40, s[14:15]
	v_cmp_gt_f32_e64 vcc, v12, v41
	v_cndmask_b32_e64 v40, v40, v14, s[14:15]
	v_cndmask_b32_e64 v13, v15, v53, s[14:15]
	v_cndmask_b32_e64 v53, v53, v15, s[14:15]
	v_cndmask_b32_e64 v14, v12, v41, vcc
	v_cmp_gt_f32_e64 s[14:15], v14, v42
; DI void nsa_item(const Params& p, int bk, int qb, char* smem, float Mb) {
;     ...
;             if (ncand > need) {
;                 float key[4][4];
; #pragma unroll
;                 for (int u = 0; u < 4; ++u)
; #pragma unroll
;                     for (int r = 0; r < 4; ++r) {
;                         const int j = lane + 64 * r;
;                         key[u][r] = (j >= 1 && j <= cur - 2) ? imp[(qi + u) * 260 + j] : -1.f;
;                     }
;                 for (int s = 0; s < need; ++s) {
; #pragma unroll
;                     for (int u = 0; u < 4; ++u) {
;                         const float best = wave_max(fmaxf(fmaxf(key[u][0], key[u][1]), fmaxf(key[u][2], key[u][3])));
;                         int jstar = 1 << 20;
; #pragma unroll
;                         for (int r = 3; r >= 0; --r) {
;                             const unsigned long long bm = __ballot(key[u][r] == best);
;                             if (bm) jstar = 64 * r + (int)__builtin_ctzll(bm);
;                         }
; #pragma unroll
;                         for (int r = 0; r < 4; ++r) if (lane + 64 * r == jstar) key[u][r] = -1.f;
;                         if (lane == 0) sel[(qi + u) * 16 + nforced + s] = jstar;
;                     }
;                 }
	v_cndmask_b32_e64 v41, v41, v12, vcc
	v_cndmask_b32_e64 v15, v13, v54, vcc
	v_cndmask_b32_e64 v54, v54, v13, vcc
	v_cndmask_b32_e64 v12, v14, v42, s[14:15]
	v_cmp_gt_f32_e64 vcc, v12, v43
	v_cndmask_b32_e64 v42, v42, v14, s[14:15]
	v_cndmask_b32_e64 v13, v15, v55, s[14:15]
	v_cndmask_b32_e64 v55, v55, v15, s[14:15]
	v_cndmask_b32_e64 v14, v12, v43, vcc
	v_cmp_gt_f32_e64 s[14:15], v14, v44
	v_cndmask_b32_e64 v43, v43, v12, vcc
	v_cndmask_b32_e64 v15, v13, v56, vcc
	v_cndmask_b32_e64 v56, v56, v13, vcc
	v_cndmask_b32_e64 v12, v14, v44, s[14:15]
	v_cmp_gt_f32_e64 vcc, v12, v45
	v_cndmask_b32_e64 v44, v44, v14, s[14:15]
	v_cndmask_b32_e64 v13, v15, v57, s[14:15]
	v_cndmask_b32_e64 v57, v57, v15, s[14:15]
	v_cndmask_b32_e64 v14, v12, v45, vcc
	s_nop 0
	v_cndmask_b32_e64 v45, v45, v12, vcc
	v_cndmask_b32_e64 v58, v58, v13, vcc
	v_add_u32_e32 v13, 1, v31
	v_cmp_gt_u32_e64 s[18:19], v32, v13
	v_add_u32_e32 v13, 2, v31
	s_nop 0
	v_cndmask_b32_e64 v12, -1.0, v10, s[18:19]
	v_cmp_gt_f32_e64 vcc, v12, v33
	s_nop 1
	v_cndmask_b32_e64 v14, v12, v33, vcc
	v_cmp_gt_f32_e64 s[14:15], v14, v34
	v_cndmask_b32_e64 v33, v33, v12, vcc
	v_cndmask_b32_e64 v15, v13, v46, vcc
	v_cndmask_b32_e64 v46, v46, v13, vcc
	v_cndmask_b32_e64 v12, v14, v34, s[14:15]
	v_cmp_gt_f32_e64 vcc, v12, v35
	v_cndmask_b32_e64 v34, v34, v14, s[14:15]
	v_cndmask_b32_e64 v13, v15, v47, s[14:15]
	v_cndmask_b32_e64 v47, v47, v15, s[14:15]
	v_cndmask_b32_e64 v14, v12, v35, vcc
	v_cmp_gt_f32_e64 s[14:15], v14, v36
	v_cndmask_b32_e64 v35, v35, v12, vcc
	v_cndmask_b32_e64 v15, v13, v48, vcc
	v_cndmask_b32_e64 v48, v48, v13, vcc
	v_cndmask_b32_e64 v12, v14, v36, s[14:15]
	v_cmp_gt_f32_e64 vcc, v12, v37
	v_cndmask_b32_e64 v36, v36, v14, s[14:15]
	v_cndmask_b32_e64 v13, v15, v49, s[14:15]
	v_cndmask_b32_e64 v49, v49, v15, s[14:15]
	v_cndmask_b32_e64 v14, v12, v37, vcc
	v_cmp_gt_f32_e64 s[14:15], v14, v38
	v_cndmask_b32_e64 v37, v37, v12, vcc
	v_cndmask_b32_e64 v15, v13, v50, vcc
	v_cndmask_b32_e64 v50, v50, v13, vcc
	v_cndmask_b32_e64 v12, v14, v38, s[14:15]
	v_cmp_gt_f32_e64 vcc, v12, v39
	v_cndmask_b32_e64 v38, v38, v14, s[14:15]
	v_cndmask_b32_e64 v13, v15, v51, s[14:15]
	v_cndmask_b32_e64 v51, v51, v15, s[14:15]
	v_cndmask_b32_e64 v14, v12, v39, vcc
	v_cmp_gt_f32_e64 s[14:15], v14, v40
	v_cndmask_b32_e64 v39, v39, v12, vcc
	v_cndmask_b32_e64 v15, v13, v52, vcc
	v_cndmask_b32_e64 v52, v52, v13, vcc
	v_cndmask_b32_e64 v12, v14, v40, s[14:15]
	v_cmp_gt_f32_e64 vcc, v12, v41
	v_cndmask_b32_e64 v40, v40, v14, s[14:15]
	v_cndmask_b32_e64 v13, v15, v53, s[14:15]
	v_cndmask_b32_e64 v53, v53, v15, s[14:15]
	v_cndmask_b32_e64 v14, v12, v41, vcc
	v_cmp_gt_f32_e64 s[14:15], v14, v42
	v_cndmask_b32_e64 v41, v41, v12, vcc
	v_cndmask_b32_e64 v15, v13, v54, vcc
	v_cndmask_b32_e64 v54, v54, v13, vcc
	v_cndmask_b32_e64 v12, v14, v42, s[14:15]
	v_cmp_gt_f32_e64 vcc, v12, v43
	v_cndmask_b32_e64 v42, v42, v14, s[14:15]
	v_cndmask_b32_e64 v13, v15, v55, s[14:15]
	v_cndmask_b32_e64 v55, v55, v15, s[14:15]
	v_cndmask_b32_e64 v14, v12, v43, vcc
	v_cmp_gt_f32_e64 s[14:15], v14, v44
	v_cndmask_b32_e64 v43, v43, v12, vcc
	v_cndmask_b32_e64 v15, v13, v56, vcc
	v_cndmask_b32_e64 v56, v56, v13, vcc
	v_cndmask_b32_e64 v12, v14, v44, s[14:15]
	v_cmp_gt_f32_e64 vcc, v12, v45
	v_cndmask_b32_e64 v44, v44, v14, s[14:15]
	v_cndmask_b32_e64 v13, v15, v57, s[14:15]
	v_cndmask_b32_e64 v57, v57, v15, s[14:15]
	v_cndmask_b32_e64 v14, v12, v45, vcc
	s_nop 0
	v_cndmask_b32_e64 v45, v45, v12, vcc
	v_cndmask_b32_e64 v58, v58, v13, vcc
	v_add_u32_e32 v13, 2, v31
	v_cmp_gt_u32_e64 s[18:19], v32, v13
	v_add_u32_e32 v13, 3, v31
	s_nop 0
	v_cndmask_b32_e64 v12, -1.0, v11, s[18:19]
	v_cmp_gt_f32_e64 vcc, v12, v33
	s_nop 1
	v_cndmask_b32_e64 v14, v12, v33, vcc
	v_cmp_gt_f32_e64 s[14:15], v14, v34
	v_cndmask_b32_e64 v33, v33, v12, vcc
	v_cndmask_b32_e64 v15, v13, v46, vcc
	v_cndmask_b32_e64 v46, v46, v13, vcc
	v_cndmask_b32_e64 v12, v14, v34, s[14:15]
	v_cmp_gt_f32_e64 vcc, v12, v35
	v_cndmask_b32_e64 v34, v34, v14, s[14:15]
	v_cndmask_b32_e64 v13, v15, v47, s[14:15]
	v_cndmask_b32_e64 v47, v47, v15, s[14:15]
	v_cndmask_b32_e64 v14, v12, v35, vcc
	v_cmp_gt_f32_e64 s[14:15], v14, v36
	v_cndmask_b32_e64 v35, v35, v12, vcc
	v_cndmask_b32_e64 v15, v13, v48, vcc
	v_cndmask_b32_e64 v48, v48, v13, vcc
	v_cndmask_b32_e64 v12, v14, v36, s[14:15]
	v_cmp_gt_f32_e64 vcc, v12, v37
	v_cndmask_b32_e64 v36, v36, v14, s[14:15]
	v_cndmask_b32_e64 v13, v15, v49, s[14:15]
	v_cndmask_b32_e64 v49, v49, v15, s[14:15]
	v_cndmask_b32_e64 v14, v12, v37, vcc
	v_cmp_gt_f32_e64 s[14:15], v14, v38
	v_cndmask_b32_e64 v37, v37, v12, vcc
	v_cndmask_b32_e64 v15, v13, v50, vcc
	v_cndmask_b32_e64 v50, v50, v13, vcc
	v_cndmask_b32_e64 v12, v14, v38, s[14:15]
	v_cmp_gt_f32_e64 vcc, v12, v39
	v_cndmask_b32_e64 v38, v38, v14, s[14:15]
	v_cndmask_b32_e64 v13, v15, v51, s[14:15]
	v_cndmask_b32_e64 v51, v51, v15, s[14:15]
	v_cndmask_b32_e64 v14, v12, v39, vcc
	v_cmp_gt_f32_e64 s[14:15], v14, v40
	v_cndmask_b32_e64 v39, v39, v12, vcc
	v_cndmask_b32_e64 v15, v13, v52, vcc
	v_cndmask_b32_e64 v52, v52, v13, vcc
	v_cndmask_b32_e64 v12, v14, v40, s[14:15]
	v_cmp_gt_f32_e64 vcc, v12, v41
	v_cndmask_b32_e64 v40, v40, v14, s[14:15]
	v_cndmask_b32_e64 v13, v15, v53, s[14:15]
	v_cndmask_b32_e64 v53, v53, v15, s[14:15]
	v_cndmask_b32_e64 v14, v12, v41, vcc
	v_cmp_gt_f32_e64 s[14:15], v14, v42
	v_cndmask_b32_e64 v41, v41, v12, vcc
	v_cndmask_b32_e64 v15, v13, v54, vcc
	v_cndmask_b32_e64 v54, v54, v13, vcc
	v_cndmask_b32_e64 v12, v14, v42, s[14:15]
	v_cmp_gt_f32_e64 vcc, v12, v43
	v_cndmask_b32_e64 v42, v42, v14, s[14:15]
	v_cndmask_b32_e64 v13, v15, v55, s[14:15]
	v_cndmask_b32_e64 v55, v55, v15, s[14:15]
	v_cndmask_b32_e64 v14, v12, v43, vcc
	v_cmp_gt_f32_e64 s[14:15], v14, v44
	v_cndmask_b32_e64 v43, v43, v12, vcc
	v_cndmask_b32_e64 v15, v13, v56, vcc
	v_cndmask_b32_e64 v56, v56, v13, vcc
	v_cndmask_b32_e64 v12, v14, v44, s[14:15]
	v_cmp_gt_f32_e64 vcc, v12, v45
	v_cndmask_b32_e64 v44, v44, v14, s[14:15]
	v_cndmask_b32_e64 v13, v15, v57, s[14:15]
	v_cndmask_b32_e64 v57, v57, v15, s[14:15]
	v_cndmask_b32_e64 v14, v12, v45, vcc
	s_nop 0
	v_cndmask_b32_e64 v45, v45, v12, vcc
	v_cndmask_b32_e64 v58, v58, v13, vcc
	v_add_u32_e32 v31, 4, v31
	s_add_i32 s26, s26, 1
	s_cmp_lt_u32 s26, 16
	s_cbranch_scc1 .Ltopk_loop
; DI void nsa_item(const Params& p, int bk, int qb, char* smem, float Mb) {
;     ...
;             if (ncand > need) {
;                 float key[4][4];
; #pragma unroll
;                 for (int u = 0; u < 4; ++u)
; #pragma unroll
;                     for (int r = 0; r < 4; ++r) {
;                         const int j = lane + 64 * r;
;                         key[u][r] = (j >= 1 && j <= cur - 2) ? imp[(qi + u) * 260 + j] : -1.f;
;                     }
;                 for (int s = 0; s < need; ++s) {
; #pragma unroll
;                     for (int u = 0; u < 4; ++u) {
;                         const float best = wave_max(fmaxf(fmaxf(key[u][0], key[u][1]), fmaxf(key[u][2], key[u][3])));
;                         int jstar = 1 << 20;
; #pragma unroll
;                         for (int r = 3; r >= 0; --r) {
;                             const unsigned long long bm = __ballot(key[u][r] == best);
;                             if (bm) jstar = 64 * r + (int)__builtin_ctzll(bm);
;                         }
; #pragma unroll
;                         for (int r = 0; r < 4; ++r) if (lane + 64 * r == jstar) key[u][r] = -1.f;
;                         if (lane == 0) sel[(qi + u) * 16 + nforced + s] = jstar;
;                     }
;                 }
	v_mul_u32_u24_e32 v10, 104, v146
	v_add_u32_e32 v10, s90, v10
	ds_write2_b32 v10, v33, v46 offset0:0 offset1:1
	ds_write2_b32 v10, v34, v47 offset0:2 offset1:3
	ds_write2_b32 v10, v35, v48 offset0:4 offset1:5
	ds_write2_b32 v10, v36, v49 offset0:6 offset1:7
	ds_write2_b32 v10, v37, v50 offset0:8 offset1:9
	ds_write2_b32 v10, v38, v51 offset0:10 offset1:11
	ds_write2_b32 v10, v39, v52 offset0:12 offset1:13
	ds_write2_b32 v10, v40, v53 offset0:14 offset1:15
	ds_write2_b32 v10, v41, v54 offset0:16 offset1:17
	ds_write2_b32 v10, v42, v55 offset0:18 offset1:19
	ds_write2_b32 v10, v43, v56 offset0:20 offset1:21
	ds_write2_b32 v10, v44, v57 offset0:22 offset1:23
	ds_write2_b32 v10, v45, v58 offset0:24 offset1:25
	v_xor_b32_e32 v9, 16, v146
	v_mul_u32_u24_e32 v9, 104, v9
	v_add_u32_e32 v9, s90, v9
	s_waitcnt lgkmcnt(0)
	s_mov_b32 s26, 0
.Ltopk_m0:
	ds_read_b64 v[12:13], v9
	v_add_u32_e32 v9, 8, v9
	s_waitcnt lgkmcnt(0)
	v_cmp_gt_f32_e64 vcc, v12, v33
	s_nop 1
	v_cndmask_b32_e64 v14, v12, v33, vcc
	v_cmp_gt_f32_e64 s[14:15], v14, v34
	v_cndmask_b32_e64 v33, v33, v12, vcc
	v_cndmask_b32_e64 v15, v13, v46, vcc
	v_cndmask_b32_e64 v46, v46, v13, vcc
	v_cndmask_b32_e64 v12, v14, v34, s[14:15]
	v_cmp_gt_f32_e64 vcc, v12, v35
	v_cndmask_b32_e64 v34, v34, v14, s[14:15]
	v_cndmask_b32_e64 v13, v15, v47, s[14:15]
	v_cndmask_b32_e64 v47, v47, v15, s[14:15]
	v_cndmask_b32_e64 v14, v12, v35, vcc
	v_cmp_gt_f32_e64 s[14:15], v14, v36
	v_cndmask_b32_e64 v35, v35, v12, vcc
	v_cndmask_b32_e64 v15, v13, v48, vcc
	v_cndmask_b32_e64 v48, v48, v13, vcc
	v_cndmask_b32_e64 v12, v14, v36, s[14:15]
	v_cmp_gt_f32_e64 vcc, v12, v37
	v_cndmask_b32_e64 v36, v36, v14, s[14:15]
	v_cndmask_b32_e64 v13, v15, v49, s[14:15]
	v_cndmask_b32_e64 v49, v49, v15, s[14:15]
	v_cndmask_b32_e64 v14, v12, v37, vcc
	v_cmp_gt_f32_e64 s[14:15], v14, v38
	v_cndmask_b32_e64 v37, v37, v12, vcc
	v_cndmask_b32_e64 v15, v13, v50, vcc
	v_cndmask_b32_e64 v50, v50, v13, vcc
	v_cndmask_b32_e64 v12, v14, v38, s[14:15]
	v_cmp_gt_f32_e64 vcc, v12, v39
	v_cndmask_b32_e64 v38, v38, v14, s[14:15]
	v_cndmask_b32_e64 v13, v15, v51, s[14:15]
	v_cndmask_b32_e64 v51, v51, v15, s[14:15]
	v_cndmask_b32_e64 v14, v12, v39, vcc
	v_cmp_gt_f32_e64 s[14:15], v14, v40
	v_cndmask_b32_e64 v39, v39, v12, vcc
	v_cndmask_b32_e64 v15, v13, v52, vcc
	v_cndmask_b32_e64 v52, v52, v13, vcc
	v_cndmask_b32_e64 v12, v14, v40, s[14:15]
	v_cmp_gt_f32_e64 vcc, v12, v41
	v_cndmask_b32_e64 v40, v40, v14, s[14:15]
	v_cndmask_b32_e64 v13, v15, v53, s[14:15]
	v_cndmask_b32_e64 v53, v53, v15, s[14:15]
	v_cndmask_b32_e64 v14, v12, v41, vcc
	v_cmp_gt_f32_e64 s[14:15], v14, v42
	v_cndmask_b32_e64 v41, v41, v12, vcc
	v_cndmask_b32_e64 v15, v13, v54, vcc
	v_cndmask_b32_e64 v54, v54, v13, vcc
	v_cndmask_b32_e64 v12, v14, v42, s[14:15]
	v_cmp_gt_f32_e64 vcc, v12, v43
	v_cndmask_b32_e64 v42, v42, v14, s[14:15]
	v_cndmask_b32_e64 v13, v15, v55, s[14:15]
	v_cndmask_b32_e64 v55, v55, v15, s[14:15]
	v_cndmask_b32_e64 v14, v12, v43, vcc
	v_cmp_gt_f32_e64 s[14:15], v14, v44
	v_cndmask_b32_e64 v43, v43, v12, vcc
	v_cndmask_b32_e64 v15, v13, v56, vcc
	v_cndmask_b32_e64 v56, v56, v13, vcc
	v_cndmask_b32_e64 v12, v14, v44, s[14:15]
	v_cmp_gt_f32_e64 vcc, v12, v45
	v_cndmask_b32_e64 v44, v44, v14, s[14:15]
	v_cndmask_b32_e64 v13, v15, v57, s[14:15]
	v_cndmask_b32_e64 v57, v57, v15, s[14:15]
	v_cndmask_b32_e64 v14, v12, v45, vcc
	s_nop 0
	v_cndmask_b32_e64 v45, v45, v12, vcc
	v_cndmask_b32_e64 v58, v58, v13, vcc
	s_add_i32 s26, s26, 1
	s_cmp_lt_u32 s26, 13
	s_cbranch_scc1 .Ltopk_m0
	ds_write2_b32 v10, v33, v46 offset0:0 offset1:1
	ds_write2_b32 v10, v34, v47 offset0:2 offset1:3
	ds_write2_b32 v10, v35, v48 offset0:4 offset1:5
	ds_write2_b32 v10, v36, v49 offset0:6 offset1:7
	ds_write2_b32 v10, v37, v50 offset0:8 offset1:9
	ds_write2_b32 v10, v38, v51 offset0:10 offset1:11
	ds_write2_b32 v10, v39, v52 offset0:12 offset1:13
	ds_write2_b32 v10, v40, v53 offset0:14 offset1:15
	ds_write2_b32 v10, v41, v54 offset0:16 offset1:17
	ds_write2_b32 v10, v42, v55 offset0:18 offset1:19
	ds_write2_b32 v10, v43, v56 offset0:20 offset1:21
	ds_write2_b32 v10, v44, v57 offset0:22 offset1:23
	ds_write2_b32 v10, v45, v58 offset0:24 offset1:25
	v_xor_b32_e32 v9, 32, v146
	v_mul_u32_u24_e32 v9, 104, v9
	v_add_u32_e32 v9, s90, v9
	s_waitcnt lgkmcnt(0)
	s_mov_b32 s26, 0
; DI void nsa_item(const Params& p, int bk, int qb, char* smem, float Mb) {
;     ...
;         for (int qi = 0; qi < 16; qi += 4) {
; #pragma unroll
;             for (int u = 0; u < 4; ++u)
;                 if (lane < 16) {
;                     int v = -1;
;                     if (ncand <= need && lane >= nforced && lane - nforced < ncand) v = lane - nforced + 1;
;                     sel[(qi + u) * 16 + lane] = v;
;                 }
;             if (ncand > need) {
;                 float key[4][4];
; #pragma unroll
;                 for (int u = 0; u < 4; ++u)
; #pragma unroll
;                     for (int r = 0; r < 4; ++r) {
;                         const int j = lane + 64 * r;
;                         key[u][r] = (j >= 1 && j <= cur - 2) ? imp[(qi + u) * 260 + j] : -1.f;
;                     }
;                 for (int s = 0; s < need; ++s) {
; #pragma unroll
;                     for (int u = 0; u < 4; ++u) {
;                         const float best = wave_max(fmaxf(fmaxf(key[u][0], key[u][1]), fmaxf(key[u][2], key[u][3])));
;                         int jstar = 1 << 20;
; #pragma unroll
;                         for (int r = 3; r >= 0; --r) {
;                             const unsigned long long bm = __ballot(key[u][r] == best);
;                             if (bm) jstar = 64 * r + (int)__builtin_ctzll(bm);
;                         }
; #pragma unroll
;                         for (int r = 0; r < 4; ++r) if (lane + 64 * r == jstar) key[u][r] = -1.f;
;                         if (lane == 0) sel[(qi + u) * 16 + nforced + s] = jstar;
;                     }
;                 }
.Ltopk_m1:
	ds_read_b64 v[12:13], v9
	v_add_u32_e32 v9, 8, v9
	s_waitcnt lgkmcnt(0)
	v_cmp_gt_f32_e64 vcc, v12, v33
	s_nop 1
	v_cndmask_b32_e64 v14, v12, v33, vcc
	v_cmp_gt_f32_e64 s[14:15], v14, v34
	v_cndmask_b32_e64 v33, v33, v12, vcc
	v_cndmask_b32_e64 v15, v13, v46, vcc
	v_cndmask_b32_e64 v46, v46, v13, vcc
	v_cndmask_b32_e64 v12, v14, v34, s[14:15]
	v_cmp_gt_f32_e64 vcc, v12, v35
	v_cndmask_b32_e64 v34, v34, v14, s[14:15]
	v_cndmask_b32_e64 v13, v15, v47, s[14:15]
	v_cndmask_b32_e64 v47, v47, v15, s[14:15]
	v_cndmask_b32_e64 v14, v12, v35, vcc
	v_cmp_gt_f32_e64 s[14:15], v14, v36
	v_cndmask_b32_e64 v35, v35, v12, vcc
	v_cndmask_b32_e64 v15, v13, v48, vcc
	v_cndmask_b32_e64 v48, v48, v13, vcc
	v_cndmask_b32_e64 v12, v14, v36, s[14:15]
	v_cmp_gt_f32_e64 vcc, v12, v37
	v_cndmask_b32_e64 v36, v36, v14, s[14:15]
	v_cndmask_b32_e64 v13, v15, v49, s[14:15]
	v_cndmask_b32_e64 v49, v49, v15, s[14:15]
	v_cndmask_b32_e64 v14, v12, v37, vcc
	v_cmp_gt_f32_e64 s[14:15], v14, v38
	v_cndmask_b32_e64 v37, v37, v12, vcc
	v_cndmask_b32_e64 v15, v13, v50, vcc
	v_cndmask_b32_e64 v50, v50, v13, vcc
	v_cndmask_b32_e64 v12, v14, v38, s[14:15]
	v_cmp_gt_f32_e64 vcc, v12, v39
	v_cndmask_b32_e64 v38, v38, v14, s[14:15]
	v_cndmask_b32_e64 v13, v15, v51, s[14:15]
	v_cndmask_b32_e64 v51, v51, v15, s[14:15]
	v_cndmask_b32_e64 v14, v12, v39, vcc
	v_cmp_gt_f32_e64 s[14:15], v14, v40
	v_cndmask_b32_e64 v39, v39, v12, vcc
	v_cndmask_b32_e64 v15, v13, v52, vcc
	v_cndmask_b32_e64 v52, v52, v13, vcc
	v_cndmask_b32_e64 v12, v14, v40, s[14:15]
	v_cmp_gt_f32_e64 vcc, v12, v41
	v_cndmask_b32_e64 v40, v40, v14, s[14:15]
	v_cndmask_b32_e64 v13, v15, v53, s[14:15]
	v_cndmask_b32_e64 v53, v53, v15, s[14:15]
	v_cndmask_b32_e64 v14, v12, v41, vcc
	v_cmp_gt_f32_e64 s[14:15], v14, v42
	v_cndmask_b32_e64 v41, v41, v12, vcc
	v_cndmask_b32_e64 v15, v13, v54, vcc
	v_cndmask_b32_e64 v54, v54, v13, vcc
	v_cndmask_b32_e64 v12, v14, v42, s[14:15]
	v_cmp_gt_f32_e64 vcc, v12, v43
	v_cndmask_b32_e64 v42, v42, v14, s[14:15]
	v_cndmask_b32_e64 v13, v15, v55, s[14:15]
	v_cndmask_b32_e64 v55, v55, v15, s[14:15]
	v_cndmask_b32_e64 v14, v12, v43, vcc
	v_cmp_gt_f32_e64 s[14:15], v14, v44
	v_cndmask_b32_e64 v43, v43, v12, vcc
	v_cndmask_b32_e64 v15, v13, v56, vcc
	v_cndmask_b32_e64 v56, v56, v13, vcc
	v_cndmask_b32_e64 v12, v14, v44, s[14:15]
	v_cmp_gt_f32_e64 vcc, v12, v45
	v_cndmask_b32_e64 v44, v44, v14, s[14:15]
	v_cndmask_b32_e64 v13, v15, v57, s[14:15]
	v_cndmask_b32_e64 v57, v57, v15, s[14:15]
	v_cndmask_b32_e64 v14, v12, v45, vcc
	s_nop 0
	v_cndmask_b32_e64 v45, v45, v12, vcc
	v_cndmask_b32_e64 v58, v58, v13, vcc
	s_add_i32 s26, s26, 1
	s_cmp_lt_u32 s26, 13
	s_cbranch_scc1 .Ltopk_m1
	s_mov_b64 exec, 0xffff
	v_lshl_add_u32 v9, v28, 6, s90
	ds_write_b32 v9, v46 offset:16652
	ds_write_b32 v9, v47 offset:16656
	ds_write_b32 v9, v48 offset:16660
	ds_write_b32 v9, v49 offset:16664
	ds_write_b32 v9, v50 offset:16668
	ds_write_b32 v9, v51 offset:16672
	ds_write_b32 v9, v52 offset:16676
	ds_write_b32 v9, v53 offset:16680
	ds_write_b32 v9, v54 offset:16684
	ds_write_b32 v9, v55 offset:16688
	ds_write_b32 v9, v56 offset:16692
	ds_write_b32 v9, v57 offset:16696
	ds_write_b32 v9, v58 offset:16700
	s_mov_b64 exec, s[22:23]
	s_mov_b64 vcc, s[20:21]
